# unitM QK steady-state loop: K-fragment LDS reads issued two MFMAs earlier with re-derived counted lgkmcnt waits
# speedup vs baseline: 1.0019x; 1.0019x over previous
; __device__ __forceinline__ float swap32_max(float v) { auto rr = __builtin_amdgcn_permlane32_swap(__float_as_uint(v), __float_as_uint(v), false, false); return fmaxf(__uint_as_float(rr[0]), __uint_as_float(rr[1])); }
; __device__ __forceinline__ float max3f(float a, float b, float c) { float r; asm("v_max3_f32 %0, %1, %2, %3" : "=v"(r) : "v"(a), "v"(b), "v"(c)); return r; }
; __device__ __forceinline__ int crowc(int r) { return (r & 3) + 8 * (r >> 2); }
; template <int D, int DV, bool TAB, bool BITS, int KT> ...
;     ...
; #pragma unroll
;                     for (int r = 0; r < 16; ++r) { p0[r] = nm; p1[r] = nm; }
;                 }
;                 if (BITS) {
; #pragma unroll
;                     for (int r = 0; r < 16; ++r) { const int off = crowc(r); if (!((w0 >> off) & 1u)) p0[r] = NEGV; if (!((w1 >> off) & 1u)) p1[r] = NEGV; } }
; #pragma unroll
;                 for (int k4 = 0; k4 < D / 16; k4 += KG) {
;                     bf16x8 ka[KG], kb[KG];
; #pragma unroll
;                     for (int kk = 0; kk < KG; ++kk) { ka[kk] = *(const bf16x8*)(Kl + r32 * KP + ((k4 + kk) * 16 + 8 * hi) * 2); kb[kk] = *(const bf16x8*)(Kl + (32 + r32) * KP + ((k4 + kk) * 16 + 8 * hi) * 2); }
;                     __builtin_amdgcn_sched_barrier(0);
; #pragma unroll
;                     for (int kk = 0; kk < KG; ++kk) { p0 = __builtin_amdgcn_mfma_f32_32x32x16_bf16(ka[kk], qf[k4 + kk], p0, 0, 0, 0); p1 = __builtin_amdgcn_mfma_f32_32x32x16_bf16(kb[kk], qf[k4 + kk], p1, 0, 0, 0); }
;                     __builtin_amdgcn_sched_barrier(0);
;                 }
;             }
;             asm volatile("s_nop 15\n\ts_nop 7" : "+v"(p0), "+v"(p1));
;             float mx = max3f(p0[0], p1[0], p0[1]), mx2 = max3f(p1[1], p0[2], p1[2]);
; #pragma unroll
;             for (int r = 3; r < 15; r += 2) { mx = max3f(mx, p0[r], p1[r]); mx2 = max3f(mx2, p0[r + 1], p1[r + 1]); }
;             mx = max3f(mx, p0[15], p1[15]); mx = max3f(mx, mx2, mx2);
;             mx = swap32_max(mx);
;             if (__any(mx > 8.0f)) {
;                 const float dl = fmaxf(mx, 0.f); mhat += dl;
; #pragma unroll
;                 for (int r = 0; r < 16; ++r) { p0[r] -= dl; p1[r] -= dl; }
;                 const float alpha = __builtin_amdgcn_exp2f(-dl); l_run *= alpha;
;                 if (hi == 0) wsf[r32] = alpha;
.LBB0_1189:
	v_lshl_add_u64 v[66:67], s[30:31], 0, v[202:203]
	v_add_co_u32_e32 v66, vcc, 0x38a80000, v66
	v_lshl_add_u64 v[68:69], s[30:31], 0, v[200:201]
	s_nop 0
	v_addc_co_u32_e32 v67, vcc, 0, v67, vcc
	v_add_co_u32_e32 v68, vcc, 0x38a80000, v68
	s_mul_i32 s4, s12, 0x8400
	s_nop 0
	v_addc_co_u32_e32 v69, vcc, 0, v69, vcc
	global_load_dwordx4 v[162:165], v[66:67], off
	global_load_dwordx4 v[166:169], v[68:69], off
	v_lshl_add_u64 v[66:67], s[30:31], 0, v[198:199]
	v_add_co_u32_e32 v66, vcc, 0x38a80000, v66
	v_lshl_add_u64 v[68:69], s[30:31], 0, v[196:197]
	s_nop 0
	v_addc_co_u32_e32 v67, vcc, 0, v67, vcc
	v_add_co_u32_e32 v68, vcc, 0x38a80000, v68
	v_add_u32_e32 v204, s4, v207
	s_nop 0
	v_addc_co_u32_e32 v69, vcc, 0, v69, vcc
	global_load_dwordx4 v[178:181], v[66:67], off
	global_load_dwordx4 v[182:185], v[68:69], off
	v_lshl_add_u64 v[66:67], s[30:31], 0, v[192:193]
	v_lshl_add_u64 v[68:69], s[30:31], 0, v[194:195]
	global_load_dwordx4 v[174:177], v[66:67], off
	global_load_dwordx4 v[170:173], v[68:69], off
	ds_read_b128 v[222:225], v204
	ds_read_b128 v[238:241], v204 offset:32
	ds_read_b128 v[242:245], v204 offset:16896
	ds_read_b128 v[188:191], v204 offset:16928
	v_xor_b32_e32 v66, 0x80000000, v220
	v_mov_b32_e32 v67, v66
	v_mov_b32_e32 v68, v66
	v_mov_b32_e32 v69, v66
	v_mov_b32_e32 v70, v66
	v_mov_b32_e32 v71, v66
	v_mov_b32_e32 v72, v66
	v_mov_b32_e32 v73, v66
	v_mov_b32_e32 v74, v66
	v_mov_b32_e32 v75, v66
	v_mov_b32_e32 v76, v66
	v_mov_b32_e32 v77, v66
	v_mov_b32_e32 v78, v66
	v_mov_b32_e32 v79, v66
	v_mov_b32_e32 v80, v66
	v_mov_b32_e32 v81, v66
	s_waitcnt lgkmcnt(3)
	s_nop 0
	v_mfma_f32_32x32x16_bf16 v[82:97], v[222:225], v[110:113], v[66:81]
	s_waitcnt lgkmcnt(1)
	v_mfma_f32_32x32x16_bf16 v[66:81], v[242:245], v[110:113], v[66:81]
	v_mfma_f32_32x32x16_bf16 v[82:97], v[238:241], v[106:109], v[82:97]
	s_waitcnt lgkmcnt(0)
	v_mfma_f32_32x32x16_bf16 v[66:81], v[188:191], v[106:109], v[66:81]
	ds_read_b128 v[188:191], v204 offset:64
	ds_read_b128 v[238:241], v204 offset:16960
	ds_read_b128 v[222:225], v204 offset:96
	ds_read_b128 v[242:245], v204 offset:16992
	s_waitcnt lgkmcnt(3)
	v_mfma_f32_32x32x16_bf16 v[82:97], v[188:191], v[102:105], v[82:97]
	s_waitcnt lgkmcnt(2)
	v_mfma_f32_32x32x16_bf16 v[66:81], v[238:241], v[102:105], v[66:81]
	ds_read_b128 v[188:191], v204 offset:128
	ds_read_b128 v[238:241], v204 offset:17024
	s_waitcnt lgkmcnt(3)
	v_mfma_f32_32x32x16_bf16 v[82:97], v[222:225], v[98:101], v[82:97]
	s_waitcnt lgkmcnt(2)
	v_mfma_f32_32x32x16_bf16 v[66:81], v[242:245], v[98:101], v[66:81]
	ds_read_b128 v[222:225], v204 offset:160
	ds_read_b128 v[242:245], v204 offset:17056
	s_waitcnt lgkmcnt(3)
	v_mfma_f32_32x32x16_bf16 v[82:97], v[188:191], v[114:117], v[82:97]
	s_waitcnt lgkmcnt(2)
	v_mfma_f32_32x32x16_bf16 v[66:81], v[238:241], v[114:117], v[66:81]
	ds_read_b128 v[188:191], v204 offset:192
	ds_read_b128 v[238:241], v204 offset:17088
	s_waitcnt lgkmcnt(3)
	v_mfma_f32_32x32x16_bf16 v[82:97], v[222:225], v[118:121], v[82:97]
	s_waitcnt lgkmcnt(2)
	v_mfma_f32_32x32x16_bf16 v[66:81], v[242:245], v[118:121], v[66:81]
	ds_read_b128 v[222:225], v204 offset:224
	ds_read_b128 v[242:245], v204 offset:17120
	s_waitcnt lgkmcnt(3)
	v_mfma_f32_32x32x16_bf16 v[82:97], v[188:191], v[122:125], v[82:97]
	s_waitcnt lgkmcnt(2)
	v_mfma_f32_32x32x16_bf16 v[66:81], v[238:241], v[122:125], v[66:81]
	ds_read_b128 v[188:191], v204 offset:256
	ds_read_b128 v[238:241], v204 offset:17152
	s_waitcnt lgkmcnt(3)
	v_mfma_f32_32x32x16_bf16 v[82:97], v[222:225], v[126:129], v[82:97]
	s_waitcnt lgkmcnt(2)
	v_mfma_f32_32x32x16_bf16 v[66:81], v[242:245], v[126:129], v[66:81]
	ds_read_b128 v[222:225], v204 offset:288
	ds_read_b128 v[242:245], v204 offset:17184
	s_waitcnt lgkmcnt(3)
	v_mfma_f32_32x32x16_bf16 v[82:97], v[188:191], v[130:133], v[82:97]
	s_waitcnt lgkmcnt(2)
	v_mfma_f32_32x32x16_bf16 v[66:81], v[238:241], v[130:133], v[66:81]
	ds_read_b128 v[188:191], v204 offset:320
	ds_read_b128 v[238:241], v204 offset:17216
	s_waitcnt lgkmcnt(3)
	v_mfma_f32_32x32x16_bf16 v[82:97], v[222:225], v[134:137], v[82:97]
	s_waitcnt lgkmcnt(2)
	v_mfma_f32_32x32x16_bf16 v[66:81], v[242:245], v[134:137], v[66:81]
	ds_read_b128 v[222:225], v204 offset:352
	ds_read_b128 v[242:245], v204 offset:17248
	s_waitcnt lgkmcnt(3)
	v_mfma_f32_32x32x16_bf16 v[82:97], v[188:191], v[138:141], v[82:97]
	s_waitcnt lgkmcnt(2)
	v_mfma_f32_32x32x16_bf16 v[66:81], v[238:241], v[138:141], v[66:81]
	ds_read_b128 v[188:191], v204 offset:384
	ds_read_b128 v[238:241], v204 offset:17280
	s_waitcnt lgkmcnt(3)
	v_mfma_f32_32x32x16_bf16 v[82:97], v[222:225], v[142:145], v[82:97]
	s_waitcnt lgkmcnt(2)
	v_mfma_f32_32x32x16_bf16 v[66:81], v[242:245], v[142:145], v[66:81]
	ds_read_b128 v[222:225], v204 offset:416
	ds_read_b128 v[242:245], v204 offset:17312
	s_waitcnt lgkmcnt(3)
	v_mfma_f32_32x32x16_bf16 v[82:97], v[188:191], v[146:149], v[82:97]
	s_waitcnt lgkmcnt(2)
	v_mfma_f32_32x32x16_bf16 v[66:81], v[238:241], v[146:149], v[66:81]
	ds_read_b128 v[188:191], v204 offset:448
	ds_read_b128 v[238:241], v204 offset:17344
	s_waitcnt lgkmcnt(3)
	v_mfma_f32_32x32x16_bf16 v[82:97], v[222:225], v[150:153], v[82:97]
	s_waitcnt lgkmcnt(2)
	v_mfma_f32_32x32x16_bf16 v[66:81], v[242:245], v[150:153], v[66:81]
	ds_read_b128 v[222:225], v204 offset:480
	ds_read_b128 v[242:245], v204 offset:17376
	s_waitcnt lgkmcnt(3)
	v_mfma_f32_32x32x16_bf16 v[82:97], v[188:191], v[154:157], v[82:97]
	s_waitcnt lgkmcnt(2)
	v_mfma_f32_32x32x16_bf16 v[66:81], v[238:241], v[154:157], v[66:81]
	s_waitcnt lgkmcnt(1)
	v_mfma_f32_32x32x16_bf16 v[82:97], v[222:225], v[158:161], v[82:97]
	s_waitcnt lgkmcnt(0)
	v_mfma_f32_32x32x16_bf16 v[66:81], v[242:245], v[158:161], v[66:81]
	s_nop 11
	v_max3_f32 v188, v82, v66, v83
	v_max3_f32 v189, v67, v84, v68
	v_max3_f32 v188, v188, v85, v69
	v_max3_f32 v189, v189, v86, v70
	v_max3_f32 v188, v188, v87, v71
	v_max3_f32 v189, v189, v88, v72
	v_max3_f32 v188, v188, v89, v73
	v_max3_f32 v189, v189, v90, v74
	v_max3_f32 v188, v188, v91, v75
	v_max3_f32 v189, v189, v92, v76
	v_max3_f32 v188, v188, v93, v77
	v_max3_f32 v189, v189, v94, v78
	v_max3_f32 v188, v188, v95, v79
	v_max3_f32 v189, v189, v96, v80
	v_max3_f32 v188, v188, v97, v81
	v_max3_f32 v188, v188, v189, v189
	v_mov_b32_e32 v189, v188
	s_nop 1
	v_permlane32_swap_b32_e32 v188, v189
	v_max_f32_e32 v189, v189, v189
	v_max_f32_e32 v188, v188, v188
	v_max_f32_e32 v204, v188, v189
	v_cmp_lt_f32_e32 vcc, s93, v204
	s_cbranch_vccz .LBB0_1188
	v_max_f32_e32 v188, v204, v204
	v_max_f32_e32 v204, 0, v188
	v_exp_f32_e64 v221, -v204
	s_and_saveexec_b64 s[4:5], s[6:7]
	s_cbranch_execz .LBB0_1187
	ds_write_b32 v187, v221
	s_branch .LBB0_1187
